# write-through (sc1) 16-byte H stores in the P5 up-projection epilogue, on top of v13
# speedup vs baseline: 1.0125x; 1.0028x over previous
.LBB0_879:
	s_mov_b32 s15, s77
	s_andn2_b64 vcc, exec, s[4:5]
	v_lshl_add_u32 v174, s35, 8, v147
	v_ashrrev_i32_e32 v175, 31, v174
	v_lshlrev_b64 v[130:131], 6, v[174:175]
	v_lshl_add_u64 v[130:131], v[140:141], 0, v[130:131]
	global_load_dwordx4 v[178:181], v[130:131], off
	global_load_dwordx4 v[182:185], v[130:131], off offset:1024
	global_load_dwordx4 v[192:195], v[130:131], off offset:2048
	global_load_dwordx4 v[196:199], v[130:131], off offset:3072
	s_mov_b64 s[100:101], 0x2000
	v_lshl_add_u64 v[246:247], v[130:131], 0, s[100:101]
	global_load_dwordx4 v[204:207], v[246:247], off
	global_load_dwordx4 v[208:211], v[246:247], off offset:1024
	global_load_dwordx4 v[216:219], v[246:247], off offset:2048
	global_load_dwordx4 v[224:227], v[246:247], off offset:3072
	v_or_b32_e32 v172, 16, v174
	v_ashrrev_i32_e32 v173, 31, v172
	v_or_b32_e32 v170, 32, v174
	v_ashrrev_i32_e32 v171, 31, v170
	v_or_b32_e32 v168, 48, v174
	v_ashrrev_i32_e32 v169, 31, v168
	v_add_u32_e32 v162, 0x80, v174
	v_ashrrev_i32_e32 v163, 31, v162
	v_add_u32_e32 v158, 0x90, v174
	v_ashrrev_i32_e32 v159, 31, v158
	v_add_u32_e32 v154, 0xa0, v174
	v_ashrrev_i32_e32 v155, 31, v154
	s_waitcnt vmcnt(7)
	v_mov_b64_e32 v[130:131], v[178:179]
	v_mov_b64_e32 v[132:133], v[180:181]
	v_mov_b32_e32 v150, v131
	v_mov_b32_e32 v151, v132
	v_mov_b32_e32 v131, v133
	v_pk_add_f32 v[130:131], v[150:151], v[130:131]
	s_nop 0
	v_add_f32_e32 v130, v130, v131
	ds_swizzle_b32 v131, v130 offset:swizzle(SWAP,16)
	s_waitcnt lgkmcnt(0)
	v_add_f32_e32 v130, v130, v131
	v_mov_b32_e32 v131, v130
	s_nop 1
	v_permlane32_swap_b32_e32 v130, v131
	v_add_f32_e32 v130, v130, v131
	v_fmamk_f32 v130, v130, 0x3a800000, v241
	v_rsq_f32_e32 v166, v130
	s_nop 1
	v_pk_mul_f32 v[128:129], v[128:129], v[166:167] op_sel_hi:[1,0]
	v_pk_mul_f32 v[126:127], v[126:127], v[166:167] op_sel_hi:[1,0]
	v_pk_mul_f32 v[122:123], v[122:123], v[166:167] op_sel_hi:[1,0]
	v_pk_mul_f32 v[124:125], v[124:125], v[166:167] op_sel_hi:[1,0]
	v_max_f32_e32 v126, 0, v126
	v_max_f32_e32 v122, 0, v122
	v_max_f32_e32 v127, 0, v127
	v_max_f32_e32 v123, 0, v123
	v_max_f32_e32 v128, 0, v128
	v_max_f32_e32 v129, 0, v129
	v_pk_mul_f32 v[126:127], v[126:127], v[126:127]
	v_pk_mul_f32 v[122:123], v[122:123], v[122:123]
	v_max_f32_e32 v124, 0, v124
	v_max_f32_e32 v125, 0, v125
	v_pk_mul_f32 v[128:129], v[128:129], v[128:129]
	v_pk_mul_f32 v[114:115], v[114:115], v[166:167] op_sel_hi:[1,0]
	v_pk_mul_f32 v[120:121], v[120:121], v[166:167] op_sel_hi:[1,0]
	v_pk_mul_f32 v[118:119], v[118:119], v[166:167] op_sel_hi:[1,0]
	v_pk_mul_f32 v[116:117], v[116:117], v[166:167] op_sel_hi:[1,0]
	v_max_f32_e32 v114, 0, v114
	v_max_f32_e32 v115, 0, v115
	v_max_f32_e32 v118, 0, v118
	v_max_f32_e32 v119, 0, v119
	v_max_f32_e32 v116, 0, v116
	v_max_f32_e32 v117, 0, v117
	v_pk_mul_f32 v[118:119], v[118:119], v[118:119]
	s_waitcnt vmcnt(6)
	v_mov_b64_e32 v[130:131], v[182:183]
	v_mov_b64_e32 v[132:133], v[184:185]
	v_mov_b32_e32 v150, v131
	v_mov_b32_e32 v151, v132
	v_mov_b32_e32 v131, v133
	v_pk_add_f32 v[130:131], v[150:151], v[130:131]
	s_nop 0
	v_add_f32_e32 v130, v130, v131
	ds_swizzle_b32 v131, v130 offset:swizzle(SWAP,16)
	s_waitcnt lgkmcnt(0)
	v_add_f32_e32 v130, v130, v131
	v_mov_b32_e32 v131, v130
	s_nop 1
	v_permlane32_swap_b32_e32 v130, v131
	v_add_f32_e32 v130, v130, v131
	v_fmamk_f32 v130, v130, 0x3a800000, v241
	v_rsq_f32_e32 v164, v130
	s_nop 1
	v_pk_mul_f32 v[110:111], v[110:111], v[164:165] op_sel_hi:[1,0]
	v_pk_mul_f32 v[106:107], v[106:107], v[164:165] op_sel_hi:[1,0]
	v_pk_mul_f32 v[112:113], v[112:113], v[164:165] op_sel_hi:[1,0]
	v_pk_mul_f32 v[108:109], v[108:109], v[164:165] op_sel_hi:[1,0]
	v_max_f32_e32 v110, 0, v110
	v_max_f32_e32 v106, 0, v106
	v_max_f32_e32 v111, 0, v111
	v_max_f32_e32 v107, 0, v107
	v_pk_mul_f32 v[110:111], v[110:111], v[110:111]
	v_max_f32_e32 v108, 0, v108
	v_max_f32_e32 v109, 0, v109
	v_pk_mul_f32 v[98:99], v[98:99], v[164:165] op_sel_hi:[1,0]
	v_pk_mul_f32 v[104:105], v[104:105], v[164:165] op_sel_hi:[1,0]
	v_pk_mul_f32 v[102:103], v[102:103], v[164:165] op_sel_hi:[1,0]
	v_pk_mul_f32 v[100:101], v[100:101], v[164:165] op_sel_hi:[1,0]
	v_max_f32_e32 v98, 0, v98
	v_max_f32_e32 v99, 0, v99
	v_max_f32_e32 v102, 0, v102
	v_max_f32_e32 v103, 0, v103
	v_max_f32_e32 v100, 0, v100
	v_max_f32_e32 v101, 0, v101
	v_pk_mul_f32 v[102:103], v[102:103], v[102:103]
	s_waitcnt vmcnt(5)
	v_mov_b64_e32 v[130:131], v[192:193]
	v_mov_b64_e32 v[132:133], v[194:195]
	v_mov_b32_e32 v150, v131
	v_mov_b32_e32 v151, v132
	v_mov_b32_e32 v131, v133
	v_pk_add_f32 v[130:131], v[150:151], v[130:131]
	s_nop 0
	v_add_f32_e32 v130, v130, v131
	ds_swizzle_b32 v131, v130 offset:swizzle(SWAP,16)
	s_waitcnt lgkmcnt(0)
	v_add_f32_e32 v130, v130, v131
	v_mov_b32_e32 v131, v130
	s_nop 1
	v_permlane32_swap_b32_e32 v130, v131
	v_add_f32_e32 v130, v130, v131
	v_fmamk_f32 v130, v130, 0x3a800000, v241
	v_rsq_f32_e32 v160, v130
	s_nop 1
	v_pk_mul_f32 v[94:95], v[94:95], v[160:161] op_sel_hi:[1,0]
	v_pk_mul_f32 v[90:91], v[90:91], v[160:161] op_sel_hi:[1,0]
	v_pk_mul_f32 v[96:97], v[96:97], v[160:161] op_sel_hi:[1,0]
	v_pk_mul_f32 v[92:93], v[92:93], v[160:161] op_sel_hi:[1,0]
	v_max_f32_e32 v94, 0, v94
	v_max_f32_e32 v90, 0, v90
	v_max_f32_e32 v95, 0, v95
	v_max_f32_e32 v91, 0, v91
	v_pk_mul_f32 v[94:95], v[94:95], v[94:95]
	v_max_f32_e32 v92, 0, v92
	v_max_f32_e32 v93, 0, v93
	v_pk_mul_f32 v[82:83], v[82:83], v[160:161] op_sel_hi:[1,0]
	v_pk_mul_f32 v[88:89], v[88:89], v[160:161] op_sel_hi:[1,0]
	v_pk_mul_f32 v[86:87], v[86:87], v[160:161] op_sel_hi:[1,0]
	v_pk_mul_f32 v[84:85], v[84:85], v[160:161] op_sel_hi:[1,0]
	v_max_f32_e32 v82, 0, v82
	v_max_f32_e32 v83, 0, v83
	v_max_f32_e32 v86, 0, v86
	v_max_f32_e32 v87, 0, v87
	v_max_f32_e32 v84, 0, v84
	v_max_f32_e32 v85, 0, v85
	v_pk_mul_f32 v[86:87], v[86:87], v[86:87]
	s_waitcnt vmcnt(4)
	v_mov_b64_e32 v[130:131], v[196:197]
	v_mov_b64_e32 v[132:133], v[198:199]
	v_mov_b32_e32 v150, v131
	v_mov_b32_e32 v151, v132
	v_mov_b32_e32 v131, v133
	v_pk_add_f32 v[130:131], v[150:151], v[130:131]
	s_nop 0
	v_add_f32_e32 v130, v130, v131
	ds_swizzle_b32 v131, v130 offset:swizzle(SWAP,16)
	s_waitcnt lgkmcnt(0)
	v_add_f32_e32 v130, v130, v131
	v_mov_b32_e32 v131, v130
	s_nop 1
	v_permlane32_swap_b32_e32 v130, v131
	v_add_f32_e32 v130, v130, v131
	v_fmamk_f32 v130, v130, 0x3a800000, v241
	v_rsq_f32_e32 v156, v130
	s_nop 1
	v_pk_mul_f32 v[78:79], v[78:79], v[156:157] op_sel_hi:[1,0]
	v_pk_mul_f32 v[74:75], v[74:75], v[156:157] op_sel_hi:[1,0]
	v_pk_mul_f32 v[80:81], v[80:81], v[156:157] op_sel_hi:[1,0]
	v_pk_mul_f32 v[76:77], v[76:77], v[156:157] op_sel_hi:[1,0]
	v_max_f32_e32 v78, 0, v78
	v_max_f32_e32 v74, 0, v74
	v_max_f32_e32 v79, 0, v79
	v_max_f32_e32 v75, 0, v75
	v_pk_mul_f32 v[78:79], v[78:79], v[78:79]
	v_max_f32_e32 v76, 0, v76
	v_max_f32_e32 v77, 0, v77
	v_pk_mul_f32 v[66:67], v[66:67], v[156:157] op_sel_hi:[1,0]
	v_pk_mul_f32 v[72:73], v[72:73], v[156:157] op_sel_hi:[1,0]
	v_pk_mul_f32 v[70:71], v[70:71], v[156:157] op_sel_hi:[1,0]
	v_pk_mul_f32 v[68:69], v[68:69], v[156:157] op_sel_hi:[1,0]
	v_max_f32_e32 v66, 0, v66
	v_max_f32_e32 v67, 0, v67
	v_max_f32_e32 v70, 0, v70
	v_max_f32_e32 v71, 0, v71
	v_max_f32_e32 v68, 0, v68
	v_max_f32_e32 v69, 0, v69
	v_pk_mul_f32 v[70:71], v[70:71], v[70:71]
	s_waitcnt vmcnt(3)
	v_mov_b64_e32 v[130:131], v[204:205]
	v_mov_b64_e32 v[132:133], v[206:207]
	v_mov_b32_e32 v150, v131
	v_mov_b32_e32 v151, v132
	v_mov_b32_e32 v131, v133
	v_pk_add_f32 v[130:131], v[150:151], v[130:131]
	s_nop 0
	v_add_f32_e32 v130, v130, v131
	ds_swizzle_b32 v131, v130 offset:swizzle(SWAP,16)
	s_waitcnt lgkmcnt(0)
	v_add_f32_e32 v130, v130, v131
	v_mov_b32_e32 v131, v130
	s_nop 1
	v_permlane32_swap_b32_e32 v130, v131
	v_add_f32_e32 v130, v130, v131
	v_fmamk_f32 v130, v130, 0x3a800000, v241
	v_rsq_f32_e32 v152, v130
	s_nop 1
	v_pk_mul_f32 v[62:63], v[62:63], v[152:153] op_sel_hi:[1,0]
	v_pk_mul_f32 v[58:59], v[58:59], v[152:153] op_sel_hi:[1,0]
	v_pk_mul_f32 v[64:65], v[64:65], v[152:153] op_sel_hi:[1,0]
	v_pk_mul_f32 v[60:61], v[60:61], v[152:153] op_sel_hi:[1,0]
	v_max_f32_e32 v62, 0, v62
	v_max_f32_e32 v58, 0, v58
	v_max_f32_e32 v63, 0, v63
	v_max_f32_e32 v59, 0, v59
	v_pk_mul_f32 v[62:63], v[62:63], v[62:63]
	v_max_f32_e32 v60, 0, v60
	v_max_f32_e32 v61, 0, v61
	v_pk_mul_f32 v[50:51], v[50:51], v[152:153] op_sel_hi:[1,0]
	v_pk_mul_f32 v[56:57], v[56:57], v[152:153] op_sel_hi:[1,0]
	v_pk_mul_f32 v[54:55], v[54:55], v[152:153] op_sel_hi:[1,0]
	v_pk_mul_f32 v[52:53], v[52:53], v[152:153] op_sel_hi:[1,0]
	v_max_f32_e32 v50, 0, v50
	v_max_f32_e32 v51, 0, v51
	v_max_f32_e32 v54, 0, v54
	v_max_f32_e32 v55, 0, v55
	v_max_f32_e32 v52, 0, v52
	v_max_f32_e32 v53, 0, v53
	v_pk_mul_f32 v[54:55], v[54:55], v[54:55]
	s_waitcnt vmcnt(2)
	v_mov_b64_e32 v[130:131], v[208:209]
	v_mov_b64_e32 v[132:133], v[210:211]
	v_mov_b32_e32 v150, v131
	v_mov_b32_e32 v151, v132
	v_mov_b32_e32 v131, v133
	v_pk_add_f32 v[130:131], v[150:151], v[130:131]
	s_nop 0
	v_add_f32_e32 v130, v130, v131
	ds_swizzle_b32 v131, v130 offset:swizzle(SWAP,16)
	s_waitcnt lgkmcnt(0)
	v_add_f32_e32 v130, v130, v131
	v_mov_b32_e32 v131, v130
	s_nop 1
	v_permlane32_swap_b32_e32 v130, v131
	v_add_f32_e32 v130, v130, v131
	v_fmamk_f32 v130, v130, 0x3a800000, v241
	v_rsq_f32_e32 v148, v130
	s_nop 1
	v_pk_mul_f32 v[46:47], v[46:47], v[148:149] op_sel_hi:[1,0]
	v_pk_mul_f32 v[42:43], v[42:43], v[148:149] op_sel_hi:[1,0]
	v_pk_mul_f32 v[48:49], v[48:49], v[148:149] op_sel_hi:[1,0]
	v_pk_mul_f32 v[44:45], v[44:45], v[148:149] op_sel_hi:[1,0]
	v_max_f32_e32 v46, 0, v46
	v_max_f32_e32 v42, 0, v42
	v_max_f32_e32 v47, 0, v47
	v_max_f32_e32 v43, 0, v43
	v_pk_mul_f32 v[46:47], v[46:47], v[46:47]
	v_max_f32_e32 v44, 0, v44
	v_max_f32_e32 v45, 0, v45
	v_pk_mul_f32 v[34:35], v[34:35], v[148:149] op_sel_hi:[1,0]
	v_pk_mul_f32 v[40:41], v[40:41], v[148:149] op_sel_hi:[1,0]
	v_pk_mul_f32 v[38:39], v[38:39], v[148:149] op_sel_hi:[1,0]
	v_pk_mul_f32 v[36:37], v[36:37], v[148:149] op_sel_hi:[1,0]
	v_max_f32_e32 v34, 0, v34
	v_max_f32_e32 v35, 0, v35
	v_max_f32_e32 v38, 0, v38
	v_max_f32_e32 v39, 0, v39
	v_max_f32_e32 v36, 0, v36
	v_max_f32_e32 v37, 0, v37
	v_pk_mul_f32 v[38:39], v[38:39], v[38:39]
	s_waitcnt vmcnt(1)
	v_mov_b64_e32 v[130:131], v[216:217]
	v_mov_b64_e32 v[132:133], v[218:219]
	v_mov_b32_e32 v150, v131
	v_mov_b32_e32 v151, v132
	v_mov_b32_e32 v131, v133
	v_pk_add_f32 v[130:131], v[150:151], v[130:131]
	v_add_u32_e32 v150, 0xb0, v174
	v_add_f32_e32 v130, v130, v131
	ds_swizzle_b32 v131, v130 offset:swizzle(SWAP,16)
	v_ashrrev_i32_e32 v151, 31, v150
	v_lshlrev_b64 v[174:175], 13, v[174:175]
	s_waitcnt lgkmcnt(0)
	v_add_f32_e32 v130, v130, v131
	v_mov_b32_e32 v131, v130
	s_nop 1
	v_permlane32_swap_b32_e32 v130, v131
	v_add_f32_e32 v130, v130, v131
	v_fmamk_f32 v130, v130, 0x3a800000, v241
	v_rsq_f32_e32 v146, v130
	s_nop 1
	v_pk_mul_f32 v[30:31], v[30:31], v[146:147] op_sel_hi:[1,0]
	v_pk_mul_f32 v[26:27], v[26:27], v[146:147] op_sel_hi:[1,0]
	v_pk_mul_f32 v[32:33], v[32:33], v[146:147] op_sel_hi:[1,0]
	v_pk_mul_f32 v[28:29], v[28:29], v[146:147] op_sel_hi:[1,0]
	v_max_f32_e32 v30, 0, v30
	v_max_f32_e32 v26, 0, v26
	v_max_f32_e32 v31, 0, v31
	v_max_f32_e32 v27, 0, v27
	v_pk_mul_f32 v[30:31], v[30:31], v[30:31]
	v_max_f32_e32 v28, 0, v28
	v_max_f32_e32 v29, 0, v29
	v_pk_mul_f32 v[18:19], v[18:19], v[146:147] op_sel_hi:[1,0]
	v_pk_mul_f32 v[24:25], v[24:25], v[146:147] op_sel_hi:[1,0]
	v_pk_mul_f32 v[22:23], v[22:23], v[146:147] op_sel_hi:[1,0]
	v_pk_mul_f32 v[20:21], v[20:21], v[146:147] op_sel_hi:[1,0]
	v_max_f32_e32 v18, 0, v18
	v_max_f32_e32 v19, 0, v19
	v_max_f32_e32 v22, 0, v22
	v_max_f32_e32 v23, 0, v23
	v_max_f32_e32 v20, 0, v20
	v_max_f32_e32 v21, 0, v21
	v_pk_mul_f32 v[22:23], v[22:23], v[22:23]
	s_waitcnt vmcnt(0)
	v_mov_b64_e32 v[130:131], v[224:225]
	v_mov_b64_e32 v[132:133], v[226:227]
	v_mov_b32_e32 v177, v132
	v_lshl_or_b32 v132, s34, 8, v153
	v_mov_b32_e32 v176, v131
	v_mov_b32_e32 v131, v133
	v_ashrrev_i32_e32 v133, 31, v132
	v_pk_add_f32 v[130:131], v[176:177], v[130:131]
	v_pk_mul_f32 v[176:177], v[124:125], v[124:125]
	v_cvt_pk_bf16_f32 v124, v126, v127
	v_cvt_pk_bf16_f32 v125, v128, v129
	v_cvt_pk_bf16_f32 v126, v122, v123
	v_lshl_add_u64 v[128:129], s[6:7], 0, v[174:175]
	v_lshlrev_b64 v[122:123], 1, v[132:133]
	v_cvt_pk_bf16_f32 v127, v176, v177
	v_lshl_add_u64 v[128:129], v[128:129], 0, v[122:123]
	global_store_dwordx4 v[128:129], v[124:127], off sc1
	v_add_f32_e32 v130, v130, v131
	ds_swizzle_b32 v131, v130 offset:swizzle(SWAP,16)
	v_pk_mul_f32 v[124:125], v[114:115], v[114:115]
	v_max_f32_e32 v114, 0, v120
	v_max_f32_e32 v115, 0, v121
	v_pk_mul_f32 v[120:121], v[114:115], v[114:115]
	v_pk_mul_f32 v[126:127], v[116:117], v[116:117]
	v_cvt_pk_bf16_f32 v114, v118, v119
	v_cvt_pk_bf16_f32 v115, v120, v121
	v_cvt_pk_bf16_f32 v116, v124, v125
	v_cvt_pk_bf16_f32 v117, v126, v127
	global_store_dwordx4 v[128:129], v[114:117], off offset:256 sc1
	v_pk_mul_f32 v[118:119], v[108:109], v[108:109]
	s_waitcnt lgkmcnt(0)
	v_add_f32_e32 v130, v130, v131
	v_lshlrev_b64 v[114:115], 13, v[172:173]
	v_pk_mul_f32 v[116:117], v[106:107], v[106:107]
	v_max_f32_e32 v106, 0, v112
	v_max_f32_e32 v107, 0, v113
	v_pk_mul_f32 v[112:113], v[106:107], v[106:107]
	v_cvt_pk_bf16_f32 v106, v110, v111
	v_lshl_add_u64 v[110:111], s[6:7], 0, v[114:115]
	v_cvt_pk_bf16_f32 v107, v112, v113
	v_cvt_pk_bf16_f32 v108, v116, v117
	v_cvt_pk_bf16_f32 v109, v118, v119
	v_lshl_add_u64 v[110:111], v[110:111], 0, v[122:123]
	global_store_dwordx4 v[110:111], v[106:109], off sc1
	v_mov_b32_e32 v131, v130
	s_nop 1
	v_permlane32_swap_b32_e32 v130, v131
	v_pk_mul_f32 v[106:107], v[98:99], v[98:99]
	v_max_f32_e32 v98, 0, v104
	v_max_f32_e32 v99, 0, v105
	v_pk_mul_f32 v[104:105], v[98:99], v[98:99]
	v_pk_mul_f32 v[108:109], v[100:101], v[100:101]
	v_cvt_pk_bf16_f32 v98, v102, v103
	v_cvt_pk_bf16_f32 v99, v104, v105
	v_cvt_pk_bf16_f32 v100, v106, v107
	v_cvt_pk_bf16_f32 v101, v108, v109
	global_store_dwordx4 v[110:111], v[98:101], off offset:256 sc1
	v_pk_mul_f32 v[102:103], v[92:93], v[92:93]
	v_add_f32_e32 v130, v130, v131
	v_lshlrev_b64 v[98:99], 13, v[170:171]
	v_pk_mul_f32 v[100:101], v[90:91], v[90:91]
	v_max_f32_e32 v90, 0, v96
	v_max_f32_e32 v91, 0, v97
	v_pk_mul_f32 v[96:97], v[90:91], v[90:91]
	v_cvt_pk_bf16_f32 v90, v94, v95
	v_lshl_add_u64 v[94:95], s[6:7], 0, v[98:99]
	v_cvt_pk_bf16_f32 v91, v96, v97
	v_cvt_pk_bf16_f32 v92, v100, v101
	v_cvt_pk_bf16_f32 v93, v102, v103
	v_lshl_add_u64 v[94:95], v[94:95], 0, v[122:123]
	global_store_dwordx4 v[94:95], v[90:93], off sc1
	v_fmamk_f32 v130, v130, 0x3a800000, v241
	v_rsq_f32_e32 v130, v130
	v_pk_mul_f32 v[90:91], v[82:83], v[82:83]
	v_max_f32_e32 v82, 0, v88
	v_max_f32_e32 v83, 0, v89
	v_pk_mul_f32 v[88:89], v[82:83], v[82:83]
	v_pk_mul_f32 v[92:93], v[84:85], v[84:85]
	v_cvt_pk_bf16_f32 v82, v86, v87
	v_cvt_pk_bf16_f32 v83, v88, v89
	v_cvt_pk_bf16_f32 v84, v90, v91
	v_cvt_pk_bf16_f32 v85, v92, v93
	global_store_dwordx4 v[94:95], v[82:85], off offset:256 sc1
	v_pk_mul_f32 v[86:87], v[76:77], v[76:77]
	v_pk_mul_f32 v[14:15], v[14:15], v[130:131] op_sel_hi:[1,0]
	v_lshlrev_b64 v[82:83], 13, v[168:169]
	v_pk_mul_f32 v[84:85], v[74:75], v[74:75]
	v_max_f32_e32 v74, 0, v80
	v_max_f32_e32 v75, 0, v81
	v_pk_mul_f32 v[80:81], v[74:75], v[74:75]
	v_cvt_pk_bf16_f32 v74, v78, v79
	v_lshl_add_u64 v[78:79], s[6:7], 0, v[82:83]
	v_cvt_pk_bf16_f32 v75, v80, v81
	v_cvt_pk_bf16_f32 v76, v84, v85
	v_cvt_pk_bf16_f32 v77, v86, v87
	v_lshl_add_u64 v[78:79], v[78:79], 0, v[122:123]
	global_store_dwordx4 v[78:79], v[74:77], off sc1
	v_pk_mul_f32 v[10:11], v[10:11], v[130:131] op_sel_hi:[1,0]
	v_pk_mul_f32 v[16:17], v[16:17], v[130:131] op_sel_hi:[1,0]
	v_pk_mul_f32 v[74:75], v[66:67], v[66:67]
	v_max_f32_e32 v66, 0, v72
	v_max_f32_e32 v67, 0, v73
	v_pk_mul_f32 v[72:73], v[66:67], v[66:67]
	v_pk_mul_f32 v[76:77], v[68:69], v[68:69]
	v_cvt_pk_bf16_f32 v66, v70, v71
	v_cvt_pk_bf16_f32 v67, v72, v73
	v_cvt_pk_bf16_f32 v68, v74, v75
	v_cvt_pk_bf16_f32 v69, v76, v77
	global_store_dwordx4 v[78:79], v[66:69], off offset:256 sc1
	v_pk_mul_f32 v[70:71], v[60:61], v[60:61]
	v_pk_mul_f32 v[12:13], v[12:13], v[130:131] op_sel_hi:[1,0]
	v_lshlrev_b64 v[66:67], 13, v[162:163]
	v_pk_mul_f32 v[68:69], v[58:59], v[58:59]
	v_max_f32_e32 v58, 0, v64
	v_max_f32_e32 v59, 0, v65
	v_pk_mul_f32 v[64:65], v[58:59], v[58:59]
	v_cvt_pk_bf16_f32 v58, v62, v63
	v_lshl_add_u64 v[62:63], s[6:7], 0, v[66:67]
	v_cvt_pk_bf16_f32 v59, v64, v65
	v_cvt_pk_bf16_f32 v60, v68, v69
	v_cvt_pk_bf16_f32 v61, v70, v71
	v_lshl_add_u64 v[62:63], v[62:63], 0, v[122:123]
	global_store_dwordx4 v[62:63], v[58:61], off sc1
	v_max_f32_e32 v14, 0, v14
	v_max_f32_e32 v10, 0, v10
	v_pk_mul_f32 v[58:59], v[50:51], v[50:51]
	v_max_f32_e32 v50, 0, v56
	v_max_f32_e32 v51, 0, v57
	v_pk_mul_f32 v[56:57], v[50:51], v[50:51]
	v_pk_mul_f32 v[60:61], v[52:53], v[52:53]
	v_cvt_pk_bf16_f32 v50, v54, v55
	v_cvt_pk_bf16_f32 v51, v56, v57
	v_cvt_pk_bf16_f32 v52, v58, v59
	v_cvt_pk_bf16_f32 v53, v60, v61
	global_store_dwordx4 v[62:63], v[50:53], off offset:256 sc1
	v_pk_mul_f32 v[54:55], v[44:45], v[44:45]
	v_max_f32_e32 v15, 0, v15
	v_lshlrev_b64 v[50:51], 13, v[158:159]
	v_pk_mul_f32 v[52:53], v[42:43], v[42:43]
	v_max_f32_e32 v42, 0, v48
	v_max_f32_e32 v43, 0, v49
	v_pk_mul_f32 v[48:49], v[42:43], v[42:43]
	v_cvt_pk_bf16_f32 v42, v46, v47
	v_lshl_add_u64 v[46:47], s[6:7], 0, v[50:51]
	v_cvt_pk_bf16_f32 v43, v48, v49
	v_cvt_pk_bf16_f32 v44, v52, v53
	v_cvt_pk_bf16_f32 v45, v54, v55
	v_lshl_add_u64 v[46:47], v[46:47], 0, v[122:123]
	global_store_dwordx4 v[46:47], v[42:45], off sc1
	v_max_f32_e32 v11, 0, v11
	v_pk_mul_f32 v[14:15], v[14:15], v[14:15]
	v_pk_mul_f32 v[42:43], v[34:35], v[34:35]
	v_max_f32_e32 v34, 0, v40
	v_max_f32_e32 v35, 0, v41
	v_pk_mul_f32 v[40:41], v[34:35], v[34:35]
	v_pk_mul_f32 v[44:45], v[36:37], v[36:37]
	v_cvt_pk_bf16_f32 v34, v38, v39
	v_cvt_pk_bf16_f32 v35, v40, v41
	v_cvt_pk_bf16_f32 v36, v42, v43
	v_cvt_pk_bf16_f32 v37, v44, v45
	global_store_dwordx4 v[46:47], v[34:37], off offset:256 sc1
	v_pk_mul_f32 v[38:39], v[28:29], v[28:29]
	v_max_f32_e32 v12, 0, v12
	v_lshlrev_b64 v[34:35], 13, v[154:155]
	v_pk_mul_f32 v[36:37], v[26:27], v[26:27]
	v_max_f32_e32 v26, 0, v32
	v_max_f32_e32 v27, 0, v33
	v_pk_mul_f32 v[32:33], v[26:27], v[26:27]
	v_cvt_pk_bf16_f32 v26, v30, v31
	v_lshl_add_u64 v[30:31], s[6:7], 0, v[34:35]
	v_cvt_pk_bf16_f32 v27, v32, v33
	v_cvt_pk_bf16_f32 v28, v36, v37
	v_cvt_pk_bf16_f32 v29, v38, v39
	v_lshl_add_u64 v[30:31], v[30:31], 0, v[122:123]
	global_store_dwordx4 v[30:31], v[26:29], off sc1
	v_max_f32_e32 v13, 0, v13
	v_pk_mul_f32 v[2:3], v[2:3], v[130:131] op_sel_hi:[1,0]
	v_pk_mul_f32 v[26:27], v[18:19], v[18:19]
	v_max_f32_e32 v18, 0, v24
	v_max_f32_e32 v19, 0, v25
	v_pk_mul_f32 v[24:25], v[18:19], v[18:19]
	v_pk_mul_f32 v[28:29], v[20:21], v[20:21]
	v_cvt_pk_bf16_f32 v18, v22, v23
	v_cvt_pk_bf16_f32 v19, v24, v25
	v_cvt_pk_bf16_f32 v20, v26, v27
	v_cvt_pk_bf16_f32 v21, v28, v29
	global_store_dwordx4 v[30:31], v[18:21], off offset:256 sc1
	v_pk_mul_f32 v[22:23], v[12:13], v[12:13]
	v_pk_mul_f32 v[8:9], v[8:9], v[130:131] op_sel_hi:[1,0]
	v_lshlrev_b64 v[18:19], 13, v[150:151]
	v_pk_mul_f32 v[20:21], v[10:11], v[10:11]
	v_max_f32_e32 v10, 0, v16
	v_max_f32_e32 v11, 0, v17
	v_pk_mul_f32 v[16:17], v[10:11], v[10:11]
	v_cvt_pk_bf16_f32 v10, v14, v15
	v_lshl_add_u64 v[14:15], s[6:7], 0, v[18:19]
	v_cvt_pk_bf16_f32 v11, v16, v17
	v_cvt_pk_bf16_f32 v12, v20, v21
	v_cvt_pk_bf16_f32 v13, v22, v23
	v_lshl_add_u64 v[14:15], v[14:15], 0, v[122:123]
	v_pk_mul_f32 v[6:7], v[6:7], v[130:131] op_sel_hi:[1,0]
	v_pk_mul_f32 v[4:5], v[4:5], v[130:131] op_sel_hi:[1,0]
	v_max_f32_e32 v2, 0, v2
	v_max_f32_e32 v3, 0, v3
	global_store_dwordx4 v[14:15], v[10:13], off sc1
	v_max_f32_e32 v6, 0, v6
	v_max_f32_e32 v7, 0, v7
	v_pk_mul_f32 v[10:11], v[2:3], v[2:3]
	v_max_f32_e32 v2, 0, v8
	v_max_f32_e32 v4, 0, v4
	v_max_f32_e32 v3, 0, v9
	v_max_f32_e32 v5, 0, v5
	v_pk_mul_f32 v[6:7], v[6:7], v[6:7]
	v_pk_mul_f32 v[8:9], v[2:3], v[2:3]
	v_pk_mul_f32 v[12:13], v[4:5], v[4:5]
	v_cvt_pk_bf16_f32 v2, v6, v7
	v_cvt_pk_bf16_f32 v3, v8, v9
	v_cvt_pk_bf16_f32 v4, v10, v11
	v_cvt_pk_bf16_f32 v5, v12, v13
	s_mov_b64 s[34:35], -1
	global_store_dwordx4 v[14:15], v[2:5], off offset:256 sc1
	s_cbranch_vccnz .LBB0_867
	s_andn2_b64 vcc, exec, s[0:1]
	s_cbranch_vccnz .LBB0_866
	s_barrier
	s_branch .LBB0_866
